# k-adjacent MFMA order + attention K/V prefetch loads land directly in their registers (no wait on just-issued loads) + EpiRes epilogue pipelined: second-half x loads issued as first-half groups retire
# speedup vs baseline: 1.0041x; 1.0041x over previous
.LBB0_186:
	s_ashr_i32 s2, s55, 4
	v_lshl_or_b32 v242, s56, 8, v193
	s_mul_hi_i32 s3, s2, 0x6000
	s_mulk_i32 s2, 0x6000
	s_add_u32 s2, s37, s2
	v_ashrrev_i32_e32 v243, 31, v242
	s_addc_u32 s3, s39, s3
	v_lshlrev_b64 v[144:145], 2, v[242:243]
	v_lshl_add_u64 v[104:105], s[2:3], 0, v[144:145]
	v_lshl_add_u32 v244, s55, 8, v183
	v_readlane_b32 s2, v247, 56
	v_readlane_b32 s3, v247, 57
	v_ashrrev_i32_e32 v245, 31, v244
	v_lshlrev_b64 v[146:147], 12, v[244:245]
	v_lshl_add_u64 v[144:145], s[2:3], 0, v[144:145]
	v_lshl_add_u64 v[190:191], v[144:145], 0, v[146:147]
	global_load_dwordx4 v[116:119], v[104:105], off
	global_load_dwordx4 v[112:115], v[104:105], off offset:64
	global_load_dwordx4 v[108:111], v[104:105], off offset:512
	s_nop 0
	global_load_dwordx4 v[104:107], v[104:105], off offset:576
	v_lshlrev_b32_e32 v195, 2, v242
	v_lshl_add_u32 v195, v244, 12, v195
	s_mov_b64 s[22:23], -1
	global_load_dwordx4 v[196:199], v[190:191], off
	global_load_dwordx4 v[200:203], v[190:191], off offset:64
	global_load_dwordx4 v[210:213], v[190:191], off offset:512
	global_load_dwordx4 v[214:217], v[190:191], off offset:576
	s_mov_b64 s[2:3], 0x10000
	v_lshl_add_u64 v[244:245], v[190:191], 0, s[2:3]
	global_load_dwordx4 v[218:221], v[244:245], off
	global_load_dwordx4 v[222:225], v[244:245], off offset:64
	global_load_dwordx4 v[226:229], v[244:245], off offset:512
	global_load_dwordx4 v[230:233], v[244:245], off offset:576
	s_mov_b64 s[2:3], 0x20000
	v_lshl_add_u64 v[242:243], v[190:191], 0, s[2:3]
	global_load_dwordx4 v[234:237], v[242:243], off
	global_load_dwordx4 v[238:241], v[242:243], off offset:64
	global_load_dwordx4 v[164:167], v[242:243], off offset:512
	global_load_dwordx4 v[160:163], v[242:243], off offset:576
	s_mov_b64 s[2:3], 0x30000
	v_lshl_add_u64 v[244:245], v[190:191], 0, s[2:3]
	global_load_dwordx4 v[156:159], v[244:245], off
	global_load_dwordx4 v[152:155], v[244:245], off offset:64
	global_load_dwordx4 v[148:151], v[244:245], off offset:512
	global_load_dwordx4 v[144:147], v[244:245], off offset:576
	s_waitcnt vmcnt(12)
	v_pk_fma_f32 v[142:143], v[142:143], v[118:119], v[198:199]
	v_pk_fma_f32 v[140:141], v[140:141], v[116:117], v[196:197]
	v_pk_fma_f32 v[138:139], v[138:139], v[114:115], v[202:203]
	v_pk_fma_f32 v[136:137], v[136:137], v[112:113], v[200:201]
	v_pk_fma_f32 v[134:135], v[134:135], v[110:111], v[212:213]
	v_pk_fma_f32 v[132:133], v[132:133], v[108:109], v[210:211]
	v_pk_fma_f32 v[130:131], v[130:131], v[106:107], v[216:217]
	v_pk_fma_f32 v[128:129], v[128:129], v[104:105], v[214:215]
	buffer_store_dwordx4 v[140:143], v195, s[72:75], 0 offen
	buffer_store_dwordx4 v[136:139], v195, s[72:75], 0 offen offset:64
	buffer_store_dwordx4 v[132:135], v195, s[72:75], 0 offen offset:512
	buffer_store_dwordx4 v[128:131], v195, s[72:75], 0 offen offset:576
	s_mov_b64 s[2:3], 0x80000
	v_lshl_add_u64 v[242:243], v[190:191], 0, s[2:3]
	global_load_dwordx4 v[196:199], v[242:243], off
	global_load_dwordx4 v[200:203], v[242:243], off offset:64
	global_load_dwordx4 v[210:213], v[242:243], off offset:512
	global_load_dwordx4 v[214:217], v[242:243], off offset:576
	s_waitcnt vmcnt(16)
	v_pk_fma_f32 v[126:127], v[126:127], v[118:119], v[220:221]
	v_pk_fma_f32 v[124:125], v[124:125], v[116:117], v[218:219]
	v_pk_fma_f32 v[122:123], v[122:123], v[114:115], v[224:225]
	v_pk_fma_f32 v[120:121], v[120:121], v[112:113], v[222:223]
	v_pk_fma_f32 v[102:103], v[102:103], v[110:111], v[228:229]
	v_pk_fma_f32 v[100:101], v[100:101], v[108:109], v[226:227]
	v_pk_fma_f32 v[98:99], v[98:99], v[106:107], v[232:233]
	v_pk_fma_f32 v[96:97], v[96:97], v[104:105], v[230:231]
	s_mov_b32 s2, 0x10000
	buffer_store_dwordx4 v[124:127], v195, s[72:75], s2 offen
	buffer_store_dwordx4 v[120:123], v195, s[72:75], s2 offen offset:64
	buffer_store_dwordx4 v[100:103], v195, s[72:75], s2 offen offset:512
	buffer_store_dwordx4 v[96:99], v195, s[72:75], s2 offen offset:576
	s_mov_b64 s[2:3], 0x90000
	v_lshl_add_u64 v[244:245], v[190:191], 0, s[2:3]
	global_load_dwordx4 v[218:221], v[244:245], off
	global_load_dwordx4 v[222:225], v[244:245], off offset:64
	global_load_dwordx4 v[226:229], v[244:245], off offset:512
	global_load_dwordx4 v[230:233], v[244:245], off offset:576
	s_waitcnt vmcnt(20)
	v_pk_fma_f32 v[94:95], v[94:95], v[118:119], v[236:237]
	v_pk_fma_f32 v[92:93], v[92:93], v[116:117], v[234:235]
	v_pk_fma_f32 v[90:91], v[90:91], v[114:115], v[240:241]
	v_pk_fma_f32 v[88:89], v[88:89], v[112:113], v[238:239]
	v_pk_fma_f32 v[86:87], v[86:87], v[110:111], v[166:167]
	v_pk_fma_f32 v[84:85], v[84:85], v[108:109], v[164:165]
	v_pk_fma_f32 v[74:75], v[74:75], v[106:107], v[162:163]
	v_pk_fma_f32 v[72:73], v[72:73], v[104:105], v[160:161]
	s_mov_b32 s2, 0x20000
	buffer_store_dwordx4 v[92:95], v195, s[72:75], s2 offen
	buffer_store_dwordx4 v[88:91], v195, s[72:75], s2 offen offset:64
	buffer_store_dwordx4 v[84:87], v195, s[72:75], s2 offen offset:512
	buffer_store_dwordx4 v[72:75], v195, s[72:75], s2 offen offset:576
	s_mov_b64 s[2:3], 0xa0000
	v_lshl_add_u64 v[242:243], v[190:191], 0, s[2:3]
	global_load_dwordx4 v[234:237], v[242:243], off
	global_load_dwordx4 v[238:241], v[242:243], off offset:64
	global_load_dwordx4 v[164:167], v[242:243], off offset:512
	global_load_dwordx4 v[160:163], v[242:243], off offset:576
	s_waitcnt vmcnt(24)
	v_pk_fma_f32 v[82:83], v[82:83], v[118:119], v[158:159]
	v_pk_fma_f32 v[80:81], v[80:81], v[116:117], v[156:157]
	v_pk_fma_f32 v[78:79], v[78:79], v[114:115], v[154:155]
	v_pk_fma_f32 v[76:77], v[76:77], v[112:113], v[152:153]
	v_pk_fma_f32 v[70:71], v[70:71], v[110:111], v[150:151]
	v_pk_fma_f32 v[68:69], v[68:69], v[108:109], v[148:149]
	v_pk_fma_f32 v[66:67], v[66:67], v[106:107], v[146:147]
	v_pk_fma_f32 v[64:65], v[64:65], v[104:105], v[144:145]
	s_mov_b32 s2, 0x30000
	buffer_store_dwordx4 v[80:83], v195, s[72:75], s2 offen
	buffer_store_dwordx4 v[76:79], v195, s[72:75], s2 offen offset:64
	buffer_store_dwordx4 v[68:71], v195, s[72:75], s2 offen offset:512
	buffer_store_dwordx4 v[64:67], v195, s[72:75], s2 offen offset:576
	s_mov_b64 s[2:3], 0xb0000
	v_lshl_add_u64 v[244:245], v[190:191], 0, s[2:3]
	global_load_dwordx4 v[156:159], v[244:245], off
	global_load_dwordx4 v[152:155], v[244:245], off offset:64
	global_load_dwordx4 v[148:151], v[244:245], off offset:512
	global_load_dwordx4 v[144:147], v[244:245], off offset:576
	s_waitcnt vmcnt(24)
	v_pk_fma_f32 v[62:63], v[62:63], v[118:119], v[198:199]
	v_pk_fma_f32 v[60:61], v[60:61], v[116:117], v[196:197]
	v_pk_fma_f32 v[58:59], v[58:59], v[114:115], v[202:203]
	v_pk_fma_f32 v[56:57], v[56:57], v[112:113], v[200:201]
	v_pk_fma_f32 v[54:55], v[54:55], v[110:111], v[212:213]
	v_pk_fma_f32 v[52:53], v[52:53], v[108:109], v[210:211]
	v_pk_fma_f32 v[50:51], v[50:51], v[106:107], v[216:217]
	v_pk_fma_f32 v[48:49], v[48:49], v[104:105], v[214:215]
	s_mov_b32 s2, 0x80000
	buffer_store_dwordx4 v[60:63], v195, s[72:75], s2 offen
	buffer_store_dwordx4 v[56:59], v195, s[72:75], s2 offen offset:64
	buffer_store_dwordx4 v[52:55], v195, s[72:75], s2 offen offset:512
	buffer_store_dwordx4 v[48:51], v195, s[72:75], s2 offen offset:576
	s_waitcnt vmcnt(20)
	v_pk_fma_f32 v[46:47], v[46:47], v[118:119], v[220:221]
	v_pk_fma_f32 v[44:45], v[44:45], v[116:117], v[218:219]
	v_pk_fma_f32 v[42:43], v[42:43], v[114:115], v[224:225]
	v_pk_fma_f32 v[40:41], v[40:41], v[112:113], v[222:223]
	v_pk_fma_f32 v[34:35], v[34:35], v[110:111], v[228:229]
	v_pk_fma_f32 v[32:33], v[32:33], v[108:109], v[226:227]
	v_pk_fma_f32 v[26:27], v[26:27], v[106:107], v[232:233]
	v_pk_fma_f32 v[24:25], v[24:25], v[104:105], v[230:231]
	s_mov_b32 s2, 0x90000
	buffer_store_dwordx4 v[44:47], v195, s[72:75], s2 offen
	buffer_store_dwordx4 v[40:43], v195, s[72:75], s2 offen offset:64
	buffer_store_dwordx4 v[32:35], v195, s[72:75], s2 offen offset:512
	buffer_store_dwordx4 v[24:27], v195, s[72:75], s2 offen offset:576
	s_waitcnt vmcnt(16)
	v_pk_fma_f32 v[38:39], v[38:39], v[118:119], v[236:237]
	v_pk_fma_f32 v[36:37], v[36:37], v[116:117], v[234:235]
	v_pk_fma_f32 v[30:31], v[30:31], v[114:115], v[240:241]
	v_pk_fma_f32 v[28:29], v[28:29], v[112:113], v[238:239]
	v_pk_fma_f32 v[18:19], v[18:19], v[110:111], v[166:167]
	v_pk_fma_f32 v[16:17], v[16:17], v[108:109], v[164:165]
	v_pk_fma_f32 v[10:11], v[10:11], v[106:107], v[162:163]
	v_pk_fma_f32 v[8:9], v[8:9], v[104:105], v[160:161]
	s_mov_b32 s2, 0xa0000
	buffer_store_dwordx4 v[36:39], v195, s[72:75], s2 offen
	buffer_store_dwordx4 v[28:31], v195, s[72:75], s2 offen offset:64
	buffer_store_dwordx4 v[16:19], v195, s[72:75], s2 offen offset:512
	buffer_store_dwordx4 v[8:11], v195, s[72:75], s2 offen offset:576
	s_waitcnt vmcnt(12)
	v_pk_fma_f32 v[22:23], v[22:23], v[118:119], v[158:159]
	v_pk_fma_f32 v[20:21], v[20:21], v[116:117], v[156:157]
	v_pk_fma_f32 v[14:15], v[14:15], v[114:115], v[154:155]
	v_pk_fma_f32 v[12:13], v[12:13], v[112:113], v[152:153]
	v_pk_fma_f32 v[6:7], v[6:7], v[110:111], v[150:151]
	v_pk_fma_f32 v[4:5], v[4:5], v[108:109], v[148:149]
	v_pk_fma_f32 v[2:3], v[2:3], v[106:107], v[146:147]
	v_pk_fma_f32 v[0:1], v[0:1], v[104:105], v[144:145]
	s_mov_b32 s2, 0xb0000
	buffer_store_dwordx4 v[20:23], v195, s[72:75], s2 offen
	buffer_store_dwordx4 v[12:15], v195, s[72:75], s2 offen offset:64
	buffer_store_dwordx4 v[4:7], v195, s[72:75], s2 offen offset:512
	buffer_store_dwordx4 v[0:3], v195, s[72:75], s2 offen offset:576
	s_and_b64 vcc, exec, s[4:5]
	s_cbranch_vccnz .LBB0_171
	s_andn2_b64 vcc, exec, s[16:17]
	s_cbranch_vccnz .LBB0_170
	s_barrier
	s_branch .LBB0_170

.LBB0_203:
	v_mfma_f32_32x32x16_bf16 v[32:47], v[32:35], v[112:115], 0
	v_mfma_f32_32x32x16_bf16 v[32:47], v[136:139], v[116:119], v[32:47]
	v_mfma_f32_32x32x16_bf16 v[32:47], v[132:135], v[120:123], v[32:47]
	v_mfma_f32_32x32x16_bf16 v[32:47], v[128:131], v[124:127], v[32:47]
	s_nop 11
	v_med3_f32 v128, v33, s87, v204
	v_med3_f32 v33, v36, s87, v204
	v_med3_f32 v36, v38, s87, v204
	v_exp_f32_e32 v132, v33
	v_exp_f32_e32 v134, v36
	v_med3_f32 v37, v37, s87, v204
	v_med3_f32 v129, v39, s87, v204
	v_med3_f32 v39, v40, s87, v204
	v_med3_f32 v38, v41, s87, v204
	v_exp_f32_e32 v133, v37
	v_add_f32_e32 v138, 1.0, v132
	v_med3_f32 v34, v34, s87, v204
	v_med3_f32 v35, v35, s87, v204
	v_exp_f32_e32 v41, v128
	v_exp_f32_e32 v136, v39
	v_exp_f32_e32 v139, v38
	v_add_f32_e32 v193, 1.0, v134
	v_log_f32_e32 v134, v138
	v_exp_f32_e32 v130, v34
	v_exp_f32_e32 v131, v35
	v_add_f32_e32 v174, 1.0, v133
	v_add_f32_e32 v41, 1.0, v41
	v_add_f32_e32 v195, 1.0, v136
	v_log_f32_e32 v136, v174
	v_sub_f32_e32 v174, v33, v134
	v_add_f32_e32 v33, 1.0, v139
	v_med3_f32 v42, v42, s87, v204
	v_add_f32_e32 v137, 1.0, v130
	v_add_f32_e32 v131, 1.0, v131
	v_log_f32_e32 v130, v41
	v_log_f32_e32 v213, v33
	v_exp_f32_e32 v33, v42
	v_med3_f32 v41, v43, s87, v204
	v_med3_f32 v44, v44, s87, v204
	v_exp_f32_e32 v135, v129
	v_log_f32_e32 v133, v131
	v_exp_f32_e32 v43, v41
	v_exp_f32_e32 v131, v44
	v_add_f32_e32 v33, 1.0, v33
	v_med3_f32 v46, v46, s87, v204
	v_add_f32_e32 v135, 1.0, v135
	v_log_f32_e32 v214, v33
	v_add_f32_e32 v33, 1.0, v43
	v_add_f32_e32 v43, 1.0, v131
	v_exp_f32_e32 v131, v46
	v_med3_f32 v47, v47, s87, v204
	v_log_f32_e32 v212, v135
	v_med3_f32 v216, v45, s87, v204
	v_exp_f32_e32 v135, v47
	v_exp_f32_e32 v45, v216
	v_add_f32_e32 v131, 1.0, v131
	v_log_f32_e32 v218, v131
	v_add_f32_e32 v131, 1.0, v135
	v_add_f32_e32 v45, 1.0, v45
	v_log_f32_e32 v219, v131
	v_log_f32_e32 v220, v45
	v_log_f32_e32 v132, v137
	v_log_f32_e32 v137, v195
	v_log_f32_e32 v222, v43
	v_log_f32_e32 v215, v33
	v_xor_b32_e32 v217, 0x80000000, v218
	v_mov_b32_e32 v221, v219
	v_log_f32_e32 v138, v193
	v_pk_add_f32 v[216:217], v[216:217], v[220:221] neg_lo:[0,1] neg_hi:[0,1]
	v_mov_b32_e32 v223, v220
	v_mov_b32_e32 v45, v217
	v_pk_add_f32 v[44:45], v[44:45], v[222:223] neg_lo:[0,1] neg_hi:[0,1]
	v_sub_f32_e32 v195, v39, v137
	v_xor_b32_e32 v39, 0x80000000, v214
	v_mov_b32_e32 v220, v213
	v_mov_b32_e32 v221, v215
	v_med3_f32 v32, v32, s87, v204
	v_sub_f32_e32 v43, v45, v222
	v_pk_add_f32 v[38:39], v[38:39], v[220:221] neg_lo:[0,1] neg_hi:[0,1]
	v_exp_f32_e32 v40, v32
	ds_bpermute_b32 v131, v209, v43
	v_xor_b32_e32 v220, 0x80000000, v138
	v_mov_b32_e32 v221, v39
	v_pk_add_f32 v[220:221], v[220:221], v[212:213] neg_lo:[0,1] neg_hi:[0,1]
	v_sub_f32_e32 v193, v37, v136
	v_pk_add_f32 v[136:137], v[220:221], v[136:137] neg_lo:[0,1] neg_hi:[0,1]
	ds_bpermute_b32 v135, v209, v137
	v_add_f32_e32 v40, 1.0, v40
	v_log_f32_e32 v40, v40
	s_waitcnt lgkmcnt(1)
	v_cndmask_b32_e64 v33, 0, v131, s[0:1]
	v_sub_f32_e32 v197, v47, v219
	v_add_f32_e32 v47, v191, v33
	v_add_f32_e32 v33, v43, v131
	v_sub_f32_e32 v199, v129, v212
	v_xor_b32_e32 v129, 0x80000000, v132
	v_mov_b32_e32 v131, v133
	v_pk_add_f32 v[128:129], v[128:129], v[130:131] neg_lo:[0,1] neg_hi:[0,1]
	v_add_f32_e32 v223, v191, v33
	v_sub_f32_e32 v191, v41, v215
	s_waitcnt lgkmcnt(0)
	v_pk_add_f32 v[224:225], v[136:137], v[134:135] neg_lo:[0,1] neg_hi:[0,1]
	v_mov_b32_e32 v41, v130
	v_mov_b32_e32 v33, v129
	ds_bpermute_b32 v222, v209, v224
	v_pk_add_f32 v[32:33], v[32:33], v[40:41] neg_lo:[0,1] neg_hi:[0,1]
	v_mov_b32_e32 v139, v212
	v_sub_f32_e32 v40, v33, v40
	ds_bpermute_b32 v130, v209, v40
	v_pk_add_f32 v[212:213], v[136:137], v[134:135]
	v_cndmask_b32_e64 v37, 0, v135, s[0:1]
	v_mov_b32_e32 v225, v213
	s_waitcnt lgkmcnt(1)
	v_pk_add_f32 v[134:135], v[224:225], v[222:223]
	v_cndmask_b32_e64 v137, 0, v222, s[0:1]
	v_mov_b32_e32 v41, v134
	v_mov_b32_e32 v131, v135
	v_add_f32_e32 v43, v37, v223
	v_add_f32_e32 v37, v137, v135
	v_sub_f32_e32 v137, v35, v133
	s_waitcnt lgkmcnt(0)
	v_cndmask_b32_e64 v35, 0, v130, s[0:1]
	v_pk_add_f32 v[40:41], v[40:41], v[130:131]
	s_nop 0
	v_add_f32_e32 v35, v35, v41
	v_add_f32_e32 v33, v33, v35
	v_add_f32_e32 v32, v32, v33
	v_exp_f32_e32 v130, v32
	v_add_f32_e32 v32, v129, v35
	v_add_f32_e32 v32, v128, v32
	v_exp_f32_e32 v128, v32
	v_pk_add_f32 v[32:33], v[34:35], v[132:133] neg_lo:[0,1] neg_hi:[0,1]
	s_nop 0
	v_add_f32_e32 v32, v32, v33
	v_exp_f32_e32 v34, v32
	v_add_f32_e32 v32, 0, v35
	v_add_f32_e32 v32, v137, v32
	v_exp_f32_e32 v35, v32
	v_add_f32_e32 v32, v136, v37
	v_add_f32_e32 v32, v174, v32
	v_exp_f32_e32 v129, v32
	v_add_f32_e32 v32, v220, v37
	v_add_f32_e32 v32, v193, v32
	v_exp_f32_e32 v131, v32
	v_pk_add_f32 v[32:33], v[36:37], v[138:139] neg_lo:[0,1] neg_hi:[0,1]
	s_nop 0
	v_add_f32_e32 v32, v32, v33
	v_exp_f32_e32 v36, v32
	v_add_f32_e32 v32, 0, v37
	v_add_f32_e32 v32, v199, v32
	v_exp_f32_e32 v37, v32
	v_add_f32_e32 v32, v221, v43
	v_add_f32_e32 v32, v195, v32
	v_exp_f32_e32 v132, v32
	v_add_f32_e32 v32, v39, v43
	v_add_f32_e32 v32, v38, v32
	v_exp_f32_e32 v38, v32
	v_pk_add_f32 v[32:33], v[42:43], v[214:215] neg_lo:[0,1] neg_hi:[0,1]
	s_nop 0
	v_add_f32_e32 v32, v32, v33
	v_exp_f32_e32 v39, v32
	v_add_f32_e32 v32, 0, v43
	v_add_f32_e32 v32, v191, v32
	v_exp_f32_e32 v42, v32
	v_add_f32_e32 v32, v47, v45
	v_add_f32_e32 v43, v44, v32
	v_cvt_pk_bf16_f32 v32, v130, v128
	v_cvt_pk_bf16_f32 v33, v34, v35
	v_cvt_pk_bf16_f32 v34, v129, v131
	v_cvt_pk_bf16_f32 v35, v36, v37
	v_add_f32_e32 v36, v47, v217
	v_add_f32_e32 v36, v216, v36
	v_mfma_f32_32x32x16_bf16 v[0:15], v[108:111], v[32:35], v[0:15]
	v_exp_f32_e32 v44, v36
	v_pk_add_f32 v[36:37], v[46:47], v[218:219] neg_lo:[0,1] neg_hi:[0,1]
	v_exp_f32_e32 v43, v43
	v_add_f32_e32 v36, v36, v37
	v_exp_f32_e32 v36, v36
	v_add_f32_e32 v191, v40, v41
	v_cmp_le_f32_e32 vcc, s77, v191
	v_mfma_f32_32x32x16_bf16 v[16:31], v[104:107], v[32:35], v[16:31]
	v_add_f32_e32 v32, 0, v47
	v_add_f32_e32 v32, v197, v32
	v_exp_f32_e32 v35, v32
	v_cvt_pk_bf16_f32 v32, v132, v38
	v_cvt_pk_bf16_f32 v33, v39, v42
	v_cvt_pk_bf16_f32 v34, v43, v44
	v_cvt_pk_bf16_f32 v35, v36, v35
	s_nop 1
	v_mfma_f32_32x32x16_bf16 v[0:15], v[96:99], v[32:35], v[0:15]
	v_mfma_f32_32x32x16_bf16 v[16:31], v[100:103], v[32:35], v[16:31]
	s_cbranch_vccz .LBB0_202
	s_min_u32 s2, s61, 2
	s_lshl_b32 s2, s2, 11
	s_sub_i32 s2, s60, s2
	s_ashr_i32 s3, s2, 31
	s_lshl_b64 s[56:57], s[2:3], 1
	s_mov_b32 s3, s79
	v_lshl_add_u64 v[36:37], v[200:201], 0, s[56:57]
	v_lshl_add_u64 v[38:39], s[2:3], 1, v[202:203]
	v_lshl_add_u64 v[40:41], v[202:203], 0, s[56:57]
	s_waitcnt vmcnt(4)
	v_mov_b64_e32 v[128:129], v[140:141]
	v_mov_b64_e32 v[130:131], v[142:143]
	v_mov_b64_e32 v[32:33], v[160:161]
	v_mov_b64_e32 v[34:35], v[162:163]
	v_mov_b64_e32 v[136:137], v[148:149]
	v_mov_b64_e32 v[138:139], v[150:151]
	v_mov_b64_e32 v[132:133], v[144:145]
	v_mov_b64_e32 v[134:135], v[146:147]
	global_load_dwordx4 v[160:163], v[36:37], off
	global_load_dwordx4 v[148:151], v[36:37], off offset:1024
	global_load_dwordx4 v[144:147], v[36:37], off offset:2048
	global_load_dwordx4 v[140:143], v[36:37], off offset:3072
	s_waitcnt vmcnt(4)
	v_mov_b64_e32 v[100:101], v[168:169]
	v_mov_b64_e32 v[104:105], v[164:165]
	v_mov_b64_e32 v[96:97], v[156:157]
	v_mov_b64_e32 v[108:109], v[152:153]
	v_mov_b64_e32 v[102:103], v[170:171]
	v_mov_b64_e32 v[106:107], v[166:167]
	v_mov_b64_e32 v[98:99], v[158:159]
	v_mov_b64_e32 v[110:111], v[154:155]
	global_load_dwordx4 v[152:155], v[38:39], off
	global_load_dwordx4 v[156:159], v[40:41], off offset:1024
	global_load_dwordx4 v[164:167], v[40:41], off offset:2048
	global_load_dwordx4 v[168:171], v[40:41], off offset:3072
	s_add_i32 s55, s55, -1
	s_addk_i32 s60, 0xf800
	s_add_i32 s61, s61, -1
	s_cmp_lt_u32 s55, 2
	s_cselect_b64 s[56:57], -1, 0
	s_andn2_b64 vcc, exec, s[56:57]
	s_cbranch_vccnz .LBB0_203
	s_branch .LBB0_198
